# fused LayerNorm epilogues: the LDS copy of the ln/shift/scale vectors is loaded by waves 1-4 before the row-statistics wait instead of after it
# baseline (speedup 1.0000x reference)
.LBB0_201:
	s_or_b64 exec, exec, s[0:1]
	v_readfirstlane_b32 s4, v191
	s_nop 3
	s_lshr_b32 s4, s4, 6
	s_sub_i32 s4, s4, 1
	s_cmp_gt_u32 s4, 3
	s_cbranch_scc1 .Lfln_pre_done_a
	s_add_u32 s0, s46, s10
	s_addc_u32 s1, s47, 0
	s_cmp_eq_u32 s4, 3
	s_cselect_b32 s5, 0x1000, 0
	s_add_u32 s0, s0, s5
	s_addc_u32 s1, s1, 0
	s_cmp_eq_u32 s4, 0
	s_cselect_b32 s0, s48, s0
	s_cselect_b32 s1, s49, s1
	s_cmp_eq_u32 s4, 1
	s_cselect_b32 s0, s50, s0
	s_cselect_b32 s1, s51, s1
	s_cmp_lt_u32 s4, 2
	s_cbranch_scc1 .Lfln_pre_go_a
	s_cmp_eq_u64 s[46:47], 0
	s_cbranch_scc1 .Lfln_pre_done_a

.Lfln_pre_done_a:
	s_cmp_gt_u32 s34, 63
	s_cbranch_scc1 .LBB0_218
	s_memrealtime s[0:1]
	s_lshl_b32 s4, s56, 6
	s_ashr_i32 s5, s4, 31
	s_lshl_b64 s[4:5], s[4:5], 2
	s_add_u32 s4, s18, s4
	s_addc_u32 s5, s27, s5
	s_branch .LBB0_205

.LBB0_220:
	s_or_b64 exec, exec, s[0:1]
	v_readfirstlane_b32 vcc_lo, v191
	s_nop 3
	s_lshr_b32 vcc_lo, vcc_lo, 6
	s_sub_i32 vcc_lo, vcc_lo, 1
	s_cmp_gt_u32 vcc_lo, 3
	s_cbranch_scc1 .Lfln_fill_done_a
	s_cmp_lt_u32 vcc_lo, 2
	s_cbranch_scc1 .Lfln_fill_go_a
	s_cmp_eq_u64 s[46:47], 0
	s_cbranch_scc1 .Lfln_fill_done_a
.Lfln_fill_go_a:
	s_lshl_b32 vcc_hi, vcc_lo, 10
	v_lshlrev_b32_e32 v173, 4, v214
	v_add_u32_e32 v173, vcc_hi, v173
	ds_write_b128 v173, v[168:171] offset:16384

.Lfln_pre_done_b:
	s_cmp_gt_u32 s26, 63
	s_cbranch_scc1 .LBB0_355
	s_memrealtime s[0:1]
	s_lshl_b32 s4, s56, 6
	s_ashr_i32 s5, s4, 31
	s_lshl_b64 s[4:5], s[4:5], 2
	s_add_u32 s4, s8, s4
	s_addc_u32 s5, s27, s5
	s_branch .LBB0_342
